# k26: k25 + retention scan: next-chunk address math and 10 prefetch global loads moved from before the step's first barrier to just after it (off the barrier-to-barrier critical path)
# speedup vs baseline: 1.0105x; 1.0043x over previous
; #define LAS __attribute__((address_space(3)))
; __device__ __forceinline__ unsigned cvtpk(float lo, float hi) { unsigned r; asm volatile("v_cvt_pk_bf16_f32 %0, %1, %2" : "=v"(r) : "v"(lo), "v"(hi)); return r; }
; __device__ __forceinline__ bf16x8 cat(s16x4 a, s16x4 b) { return (bf16x8){a[0], a[1], a[2], a[3], b[0], b[1], b[2], b[3]}; }
; #define MF16(a, b, c) __builtin_amdgcn_mfma_f32_16x16x32_bf16((a), (b), (c), 0, 0, 0)
; #define RBAR() do { asm volatile("s_waitcnt lgkmcnt(0)" ::: "memory"); __builtin_amdgcn_s_barrier(); asm volatile("" ::: "memory"); } while (0)
; #define SCHED() __builtin_amdgcn_sched_barrier(0)
; __device__ __forceinline__ void ret_item(LAS unsigned char* lds, const bf16_t* proj, bf16_t* OD, int b, int h, int dir, int vs, float lg2) {
;     ...
;         if (step + 1 < 64) { const int c1 = dir ? 62 - step : step + 1; const size_t t1 = (size_t)c1 * CH;
; #pragma unroll
;             for (int k = 0; k < 4; ++k) { pq[k] = *(const bf16x8*)(Qg + (t1 + qrow + 16 * k) * R_IN + qpc * 8); pk[k] = *(const bf16x8*)(Kg + (t1 + qrow + 16 * k) * R_IN + qpc * 8); }
; #pragma unroll
;             for (int k = 0; k < 2; ++k) pv[k] = *(const bf16x8*)(Vg + (t1 + vrow + 32 * k) * R_IN + vpc * 8);
;         }
;         RBAR();
;         {   f32x4 sa0 = (f32x4){0.f, 0.f, 0.f, 0.f}, sa1 = sa0;
;             s16x4 fq[2][2]; bf16x8 fk0[2], fk1[2];
;     ...
;             LDS_S(0, 0);
; #pragma unroll
;             for (int s = 0; s < 8; ++s) { if (s < 7) LDS_S((s + 1) & 1, s + 1); SCHED();
;                 const bf16x8 bq = cat(fq[s & 1][0], fq[s & 1][1]);
;                 __builtin_amdgcn_s_setprio(1); sa0 = MF16(fk0[s & 1], bq, sa0); sa1 = MF16(fk1[s & 1], bq, sa1); __builtin_amdgcn_s_setprio(0); SCHED(); }
;     ...
; #pragma unroll
;             for (int tt = 0; tt < 2; ++tt) { const f32x4 sv = tt ? sa1 : sa0; const int dt = dir ? (sjt0 + tt - sit) : (sit - sjt0 - tt);
;                 const float cs = dt <= 0 ? 1.f : dt == 1 ? c16 : dt == 2 ? c32 : c48; float w[4];
; #pragma unroll
;                 for (int r = 0; r < 4; ++r) { const bool on = dt > 0 || (dt == 0 && (dir ? (4 * g + r > l15) : (l15 >= 4 * g + r))); w[r] = on ? sv[r] * d4[r] * cs : 0.f; }
;                 u32x2 pkd; pkd.x = cvtpk(w[0], w[1]); pkd.y = cvtpk(w[2], w[3]);
;                 *(LAS u32x2*)(lds + SP + (16 * sit + l15) * RSS + (16 * (sjt0 + tt) + 4 * g) * 2) = pkd; }
.LBB0_140:
	s_add_i32 s20, s16, -1
	v_mov_b32_e32 v105, s20
	s_waitcnt lgkmcnt(0)
	s_barrier
	v_cndmask_b32_e64 v176, v104, v105, s[36:37]
	ds_read2_b64 v[104:107], v229 offset1:2
	ds_read_b128 v[108:111], v230 offset:36864
	ds_read_b128 v[112:115], v230 offset:46080
	ds_read2_b64 v[116:119], v229 offset0:8 offset1:10
	ds_read_b128 v[120:123], v230 offset:36928
	ds_read_b128 v[124:127], v230 offset:46144
	s_cmp_eq_u32 s19, -1
	s_cbranch_scc1 .Lscan_pf_skip
	s_and_b64 s[20:21], s[36:37], exec
	s_cselect_b32 s20, s16, s19
	s_ashr_i32 s21, s20, 31
	s_lshl_b64 s[20:21], s[20:21], 6
	v_lshl_add_u64 v[0:1], s[20:21], 0, v[162:163]
	v_mad_u64_u32 v[24:25], s[22:23], v0, s3, v[168:169]
	v_mad_i32_i24 v25, v1, s3, v25
	v_add_co_u32_e32 v8, vcc, s65, v24
	v_mad_u64_u32 v[26:27], s[22:23], v0, s3, v[170:171]
	s_nop 0
	v_addc_co_u32_e32 v9, vcc, 0, v25, vcc
	v_mad_i32_i24 v27, v1, s3, v27
	v_add_co_u32_e32 v12, vcc, s65, v26
	global_load_dwordx4 v[0:3], v[24:25], off
	global_load_dwordx4 v[4:7], v[26:27], off
	v_addc_co_u32_e32 v13, vcc, 0, v27, vcc
	v_add_co_u32_e32 v16, vcc, s64, v24
	v_lshl_add_u64 v[32:33], s[20:21], 0, v[166:167]
	s_nop 0
	v_addc_co_u32_e32 v17, vcc, 0, v25, vcc
	v_add_co_u32_e32 v20, vcc, s64, v26
	v_mad_u64_u32 v[34:35], s[20:21], v32, s3, v[172:173]
	s_nop 0
	v_addc_co_u32_e32 v21, vcc, 0, v27, vcc
	v_add_co_u32_e32 v24, vcc, s70, v24
	v_mad_i32_i24 v35, v33, s3, v35
	s_nop 0
	v_addc_co_u32_e32 v25, vcc, 0, v25, vcc
	v_add_co_u32_e32 v28, vcc, 0x120000, v26
	global_load_dwordx4 v[8:11], v[8:9], off
	s_nop 0
	global_load_dwordx4 v[12:15], v[12:13], off
	v_addc_co_u32_e32 v29, vcc, 0, v27, vcc
	v_add_co_u32_e32 v36, vcc, 0xc0000, v34
	global_load_dwordx4 v[16:19], v[16:17], off
	s_nop 0
	global_load_dwordx4 v[20:23], v[20:21], off
	v_addc_co_u32_e32 v37, vcc, 0, v35, vcc
	global_load_dwordx4 v[24:27], v[24:25], off
	s_nop 0
	global_load_dwordx4 v[28:31], v[28:29], off
	s_nop 0
	global_load_dwordx4 v[32:35], v[34:35], off
	s_nop 0
	global_load_dwordx4 v[36:39], v[36:37], off
.Lscan_pf_skip:
	s_setprio 1
	s_waitcnt lgkmcnt(4)
	v_mfma_f32_16x16x32_bf16 v[108:111], v[108:111], v[104:107], 0
	s_waitcnt lgkmcnt(3)
	v_mfma_f32_16x16x32_bf16 v[104:107], v[112:115], v[104:107], 0
	s_setprio 0
	ds_read2_b64 v[112:115], v229 offset0:16 offset1:18
	ds_read_b128 v[128:131], v230 offset:36992
	ds_read_b128 v[132:135], v230 offset:46208
	s_setprio 1
	s_waitcnt lgkmcnt(4)
	v_mfma_f32_16x16x32_bf16 v[108:111], v[120:123], v[116:119], v[108:111]
	s_waitcnt lgkmcnt(3)
	v_mfma_f32_16x16x32_bf16 v[104:107], v[124:127], v[116:119], v[104:107]
	s_setprio 0
	ds_read2_b64 v[116:119], v229 offset0:24 offset1:26
	ds_read_b128 v[120:123], v230 offset:37056
	ds_read_b128 v[124:127], v230 offset:46272
	s_setprio 1
	s_waitcnt lgkmcnt(4)
	v_mfma_f32_16x16x32_bf16 v[108:111], v[128:131], v[112:115], v[108:111]
	s_waitcnt lgkmcnt(3)
	v_mfma_f32_16x16x32_bf16 v[104:107], v[132:135], v[112:115], v[104:107]
	s_setprio 0
	ds_read2_b64 v[112:115], v229 offset0:32 offset1:34
	ds_read_b128 v[128:131], v230 offset:37120
	ds_read_b128 v[132:135], v230 offset:46336
	s_setprio 1
	s_waitcnt lgkmcnt(4)
	v_mfma_f32_16x16x32_bf16 v[108:111], v[120:123], v[116:119], v[108:111]
	s_waitcnt lgkmcnt(3)
	v_mfma_f32_16x16x32_bf16 v[104:107], v[124:127], v[116:119], v[104:107]
	s_setprio 0
	ds_read2_b64 v[116:119], v229 offset0:40 offset1:42
	ds_read_b128 v[120:123], v230 offset:37184
	ds_read_b128 v[124:127], v230 offset:46400
	s_setprio 1
	s_waitcnt lgkmcnt(4)
	v_mfma_f32_16x16x32_bf16 v[108:111], v[128:131], v[112:115], v[108:111]
	s_waitcnt lgkmcnt(3)
	v_mfma_f32_16x16x32_bf16 v[104:107], v[132:135], v[112:115], v[104:107]
	s_setprio 0
	ds_read2_b64 v[112:115], v229 offset0:48 offset1:50
	ds_read_b128 v[128:131], v230 offset:37248
	ds_read_b128 v[132:135], v230 offset:46464
	s_setprio 1
	s_waitcnt lgkmcnt(4)
	v_mfma_f32_16x16x32_bf16 v[108:111], v[120:123], v[116:119], v[108:111]
	s_waitcnt lgkmcnt(3)
	v_mfma_f32_16x16x32_bf16 v[104:107], v[124:127], v[116:119], v[104:107]
	s_setprio 0
	ds_read2_b64 v[116:119], v229 offset0:56 offset1:58
	ds_read_b128 v[120:123], v230 offset:37312
	ds_read_b128 v[124:127], v230 offset:46528
	s_setprio 1
	s_waitcnt lgkmcnt(4)
	v_mfma_f32_16x16x32_bf16 v[108:111], v[128:131], v[112:115], v[108:111]
	s_waitcnt lgkmcnt(3)
	v_mfma_f32_16x16x32_bf16 v[104:107], v[132:135], v[112:115], v[104:107]
	s_setprio 0
	s_setprio 1
	s_waitcnt lgkmcnt(1)
	v_mfma_f32_16x16x32_bf16 v[108:111], v[120:123], v[116:119], v[108:111]
	s_waitcnt lgkmcnt(0)
	v_mfma_f32_16x16x32_bf16 v[104:107], v[124:127], v[116:119], v[104:107]
	s_setprio 0
	s_nop 4
	v_mul_f32_e32 v108, v199, v108
	v_mul_f32_e32 v109, v200, v109
	v_mul_f32_e32 v110, v201, v110
	v_mul_f32_e32 v108, v206, v108
	v_mul_f32_e32 v109, v206, v109
	v_mul_f32_e32 v110, v206, v110
	v_mul_f32_e32 v111, v202, v111
	v_mul_f32_e32 v104, v199, v104
	v_mul_f32_e32 v105, v200, v105
	v_mul_f32_e32 v106, v201, v106
	v_cndmask_b32_e64 v108, 0, v108, s[38:39]
	v_cndmask_b32_e64 v109, 0, v109, s[40:41]
	v_cndmask_b32_e64 v110, 0, v110, s[42:43]
	v_mul_f32_e32 v111, v206, v111
	v_mul_f32_e32 v104, v207, v104
	v_mul_f32_e32 v105, v207, v105
	v_mul_f32_e32 v106, v207, v106
	v_mul_f32_e32 v107, v202, v107
	v_cndmask_b32_e64 v111, 0, v111, s[44:45]
	v_cvt_pk_bf16_f32 v108, v108, v109
	v_cvt_pk_bf16_f32 v109, v110, v111
	v_add_u32_e32 v110, s17, v205
	v_cndmask_b32_e64 v104, 0, v104, s[46:47]
	v_cndmask_b32_e64 v105, 0, v105, s[48:49]
	v_cndmask_b32_e64 v106, 0, v106, s[50:51]
	v_mul_f32_e32 v107, v207, v107
	ds_write_b64 v110, v[108:109]
	v_cndmask_b32_e64 v107, 0, v107, s[52:53]
	v_cvt_pk_bf16_f32 v104, v104, v105
	v_cvt_pk_bf16_f32 v105, v106, v107
	v_add_u32_e32 v106, s18, v205
	ds_write_b64 v106, v[104:105]
	ds_read_b128 v[104:107], v231
	ds_read_b128 v[108:111], v231 offset:64
	ds_read_b128 v[112:115], v231 offset:9216
	ds_read_b128 v[116:119], v231 offset:9280
	ds_read_b128 v[120:123], v231 offset:18432
	ds_read_b128 v[124:127], v231 offset:18496
	ds_read_b128 v[128:131], v231 offset:27648
	ds_read_b128 v[132:135], v231 offset:27712
	v_cvt_pk_bf16_f32 v136, v40, v41
	v_cvt_pk_bf16_f32 v137, v42, v43
	v_cvt_pk_bf16_f32 v138, v52, v53
	v_cvt_pk_bf16_f32 v139, v54, v55
	s_setprio 1
	s_waitcnt lgkmcnt(7)
; __device__ __forceinline__ unsigned cvtpk(float lo, float hi) { unsigned r; asm volatile("v_cvt_pk_bf16_f32 %0, %1, %2" : "=v"(r) : "v"(lo), "v"(hi)); return r; }
; #define MF16(a, b, c) __builtin_amdgcn_mfma_f32_16x16x32_bf16((a), (b), (c), 0, 0, 0)
; __device__ __forceinline__ unsigned cvtpk(float lo, float hi) { unsigned r; asm volatile("v_cvt_pk_bf16_f32 %0, %1, %2" : "=v"(r) : "v"(lo), "v"(hi)); return r; }
; #define SCHED() __builtin_amdgcn_sched_barrier(0)
; #define LDS_C(buf, s) do { _Pragma("unroll") for (int it = 0; it < 4; ++it) ca[buf][it] = *(const LAS bf16x8*)(pCq + 16 * it * RSQ + 64 * (s)); } while (0)
; __device__ __forceinline__ void ret_item(LAS unsigned char* lds, const bf16_t* proj, bf16_t* OD, int b, int h, int dir, int vs, float lg2) {
;     ...
;         for (int it = 0; it < 4; ++it) acc[it] = (f32x4){0.f, 0.f, 0.f, 0.f};
;         {   bf16x8 ca[2][4];
;     ...
;             LDS_C(0, 0);
; #pragma unroll
;             for (int s = 0; s < 8; ++s) { if (s < 7) LDS_C((s + 1) & 1, s + 1); SCHED();
;                 u32x4 bw; bw.x = cvtpk(st[2 * s][0], st[2 * s][1]); bw.y = cvtpk(st[2 * s][2], st[2 * s][3]); bw.z = cvtpk(st[2 * s + 1][0], st[2 * s + 1][1]); bw.w = cvtpk(st[2 * s + 1][2], st[2 * s + 1][3]);
;                 const bf16x8 bs = __builtin_bit_cast(bf16x8, bw);
;                 __builtin_amdgcn_s_setprio(1);
; #pragma unroll
;                 for (int it = 0; it < 4; ++it) acc[it] = MF16(bs, ca[s & 1][it], acc[it]);
;                 __builtin_amdgcn_s_setprio(0); SCHED(); }
;     ...
;         }
	v_mfma_f32_16x16x32_bf16 v[104:107], v[136:139], v[104:107], 0
	s_waitcnt lgkmcnt(5)
	v_mfma_f32_16x16x32_bf16 v[112:115], v[136:139], v[112:115], 0
	s_waitcnt lgkmcnt(3)
	v_mfma_f32_16x16x32_bf16 v[120:123], v[136:139], v[120:123], 0
	s_waitcnt lgkmcnt(1)
	v_mfma_f32_16x16x32_bf16 v[128:131], v[136:139], v[128:131], 0
	s_setprio 0
	ds_read_b128 v[136:139], v231 offset:128
	ds_read_b128 v[140:143], v231 offset:9344
	ds_read_b128 v[144:147], v231 offset:18560
	ds_read_b128 v[148:151], v231 offset:27776
	v_cvt_pk_bf16_f32 v152, v48, v49
	v_cvt_pk_bf16_f32 v153, v50, v51
	v_cvt_pk_bf16_f32 v154, v44, v45
	v_cvt_pk_bf16_f32 v155, v46, v47
	s_setprio 1
	v_mfma_f32_16x16x32_bf16 v[104:107], v[152:155], v[108:111], v[104:107]
	v_mfma_f32_16x16x32_bf16 v[108:111], v[152:155], v[116:119], v[112:115]
	v_mfma_f32_16x16x32_bf16 v[112:115], v[152:155], v[124:127], v[120:123]
	s_waitcnt lgkmcnt(4)
	v_mfma_f32_16x16x32_bf16 v[116:119], v[152:155], v[132:135], v[128:131]
	s_setprio 0
	ds_read_b128 v[120:123], v231 offset:192
	ds_read_b128 v[124:127], v231 offset:9408
	ds_read_b128 v[128:131], v231 offset:18624
	ds_read_b128 v[132:135], v231 offset:27840
	v_cvt_pk_bf16_f32 v152, v68, v69
	v_cvt_pk_bf16_f32 v153, v70, v71
	v_cvt_pk_bf16_f32 v154, v64, v65
	v_cvt_pk_bf16_f32 v155, v66, v67
	s_setprio 1
	s_waitcnt lgkmcnt(7)
	v_mfma_f32_16x16x32_bf16 v[104:107], v[152:155], v[136:139], v[104:107]
	s_waitcnt lgkmcnt(6)
	v_mfma_f32_16x16x32_bf16 v[108:111], v[152:155], v[140:143], v[108:111]
	s_waitcnt lgkmcnt(5)
	v_mfma_f32_16x16x32_bf16 v[112:115], v[152:155], v[144:147], v[112:115]
	s_waitcnt lgkmcnt(4)
	v_mfma_f32_16x16x32_bf16 v[116:119], v[152:155], v[148:151], v[116:119]
	s_setprio 0
	ds_read_b128 v[136:139], v231 offset:256
	ds_read_b128 v[140:143], v231 offset:9472
	ds_read_b128 v[144:147], v231 offset:18688
	ds_read_b128 v[148:151], v231 offset:27904
	v_cvt_pk_bf16_f32 v152, v60, v61
	v_cvt_pk_bf16_f32 v153, v62, v63
	v_cvt_pk_bf16_f32 v154, v56, v57
	v_cvt_pk_bf16_f32 v155, v58, v59
	s_setprio 1
	s_waitcnt lgkmcnt(7)
	v_mfma_f32_16x16x32_bf16 v[104:107], v[152:155], v[120:123], v[104:107]
	s_waitcnt lgkmcnt(6)
	v_mfma_f32_16x16x32_bf16 v[108:111], v[152:155], v[124:127], v[108:111]
	s_waitcnt lgkmcnt(5)
	v_mfma_f32_16x16x32_bf16 v[112:115], v[152:155], v[128:131], v[112:115]
	s_waitcnt lgkmcnt(4)
	v_mfma_f32_16x16x32_bf16 v[116:119], v[152:155], v[132:135], v[116:119]
	s_setprio 0
	ds_read_b128 v[120:123], v231 offset:320
	ds_read_b128 v[124:127], v231 offset:9536
	ds_read_b128 v[128:131], v231 offset:18752
	ds_read_b128 v[132:135], v231 offset:27968
	v_cvt_pk_bf16_f32 v152, v88, v89
	v_cvt_pk_bf16_f32 v153, v90, v91
	v_cvt_pk_bf16_f32 v154, v80, v81
	v_cvt_pk_bf16_f32 v155, v82, v83
	s_setprio 1
	s_waitcnt lgkmcnt(7)
	v_mfma_f32_16x16x32_bf16 v[104:107], v[152:155], v[136:139], v[104:107]
	s_waitcnt lgkmcnt(6)
	v_mfma_f32_16x16x32_bf16 v[108:111], v[152:155], v[140:143], v[108:111]
	s_waitcnt lgkmcnt(5)
	v_mfma_f32_16x16x32_bf16 v[112:115], v[152:155], v[144:147], v[112:115]
	s_waitcnt lgkmcnt(4)
	v_mfma_f32_16x16x32_bf16 v[116:119], v[152:155], v[148:151], v[116:119]
	s_setprio 0
	ds_read_b128 v[136:139], v231 offset:384
	ds_read_b128 v[140:143], v231 offset:9600
	ds_read_b128 v[144:147], v231 offset:18816
	ds_read_b128 v[148:151], v231 offset:28032
	v_cvt_pk_bf16_f32 v152, v76, v77
	v_cvt_pk_bf16_f32 v153, v78, v79
	v_cvt_pk_bf16_f32 v154, v72, v73
	v_cvt_pk_bf16_f32 v155, v74, v75
	s_setprio 1
	s_waitcnt lgkmcnt(7)
	v_mfma_f32_16x16x32_bf16 v[104:107], v[152:155], v[120:123], v[104:107]
	s_waitcnt lgkmcnt(6)
	v_mfma_f32_16x16x32_bf16 v[108:111], v[152:155], v[124:127], v[108:111]
	s_waitcnt lgkmcnt(5)
	v_mfma_f32_16x16x32_bf16 v[112:115], v[152:155], v[128:131], v[112:115]
	s_waitcnt lgkmcnt(4)
	v_mfma_f32_16x16x32_bf16 v[116:119], v[152:155], v[132:135], v[116:119]
	s_setprio 0
	ds_read_b128 v[120:123], v231 offset:448
	ds_read_b128 v[124:127], v231 offset:9664
	ds_read_b128 v[128:131], v231 offset:18880
	ds_read_b128 v[132:135], v231 offset:28096
	v_cvt_pk_bf16_f32 v152, v92, v93
	v_cvt_pk_bf16_f32 v153, v94, v95
	v_cvt_pk_bf16_f32 v154, v84, v85
	v_cvt_pk_bf16_f32 v155, v86, v87
	s_setprio 1
	s_waitcnt lgkmcnt(7)
	v_mfma_f32_16x16x32_bf16 v[104:107], v[152:155], v[136:139], v[104:107]
	s_waitcnt lgkmcnt(6)
	v_mfma_f32_16x16x32_bf16 v[108:111], v[152:155], v[140:143], v[108:111]
	s_waitcnt lgkmcnt(5)
	v_mfma_f32_16x16x32_bf16 v[112:115], v[152:155], v[144:147], v[112:115]
	s_waitcnt lgkmcnt(4)
	v_mfma_f32_16x16x32_bf16 v[116:119], v[152:155], v[148:151], v[116:119]
	s_setprio 0
	v_cvt_pk_bf16_f32 v136, v96, v97
	v_cvt_pk_bf16_f32 v137, v98, v99
	v_cvt_pk_bf16_f32 v138, v100, v101
	v_cvt_pk_bf16_f32 v139, v102, v103
	s_setprio 1
	s_waitcnt lgkmcnt(3)
	v_mfma_f32_16x16x32_bf16 v[104:107], v[136:139], v[120:123], v[104:107]
	s_waitcnt lgkmcnt(2)
	v_mfma_f32_16x16x32_bf16 v[108:111], v[136:139], v[124:127], v[108:111]
	s_waitcnt lgkmcnt(1)
	v_mfma_f32_16x16x32_bf16 v[112:115], v[136:139], v[128:131], v[112:115]
	s_waitcnt lgkmcnt(0)
	v_mfma_f32_16x16x32_bf16 v[116:119], v[136:139], v[132:135], v[116:119]
	s_setprio 0
	s_waitcnt lgkmcnt(0)
	s_barrier
; #define LAS __attribute__((address_space(3)))
; __device__ __forceinline__ unsigned cvtpk(float lo, float hi) { unsigned r; asm volatile("v_cvt_pk_bf16_f32 %0, %1, %2" : "=v"(r) : "v"(lo), "v"(hi)); return r; }
; __device__ __forceinline__ s16x4 trd(LAS unsigned char* p) { return __builtin_bit_cast(s16x4, __builtin_amdgcn_ds_read_tr16_b64_v4i16((LAS s16x4*)p)); }
; __device__ __forceinline__ bf16x8 cat(s16x4 a, s16x4 b) { return (bf16x8){a[0], a[1], a[2], a[3], b[0], b[1], b[2], b[3]}; }
; #define MF16(a, b, c) __builtin_amdgcn_mfma_f32_16x16x32_bf16((a), (b), (c), 0, 0, 0)
; #define SCHED() __builtin_amdgcn_sched_barrier(0)
; __device__ __forceinline__ void ret_item(LAS unsigned char* lds, const bf16_t* proj, bf16_t* OD, int b, int h, int dir, int vs, float lg2) {
;     ...
;         bf16x8 bv[2], ia[2][4];
; #pragma unroll
;         for (int s = 0; s < 2; ++s) { bv[s] = cat(trd(pVt + 32 * s * RSV), trd(pVt + (32 * s + 4) * RSV));
; #pragma unroll
;             for (int it = 0; it < 4; ++it) ia[s][it] = *(const LAS bf16x8*)(pIs + 16 * it * RSS + 64 * s); }
;         s16x4 ua[2][4][2];
;     ...
;         LDS_U(0, 0);
;         SCHED();
; #pragma unroll
;         for (int it = 0; it < 4; ++it) { const int ex = dir ? 3 - it : it; const float cq = qdl * (ex == 0 ? 1.f : ex == 1 ? c16 : ex == 2 ? c32 : c48); acc[it] = acc[it] * cq; }
; #pragma unroll
;         for (int s = 0; s < 2; ++s)
; #pragma unroll
;             for (int it = 0; it < 4; ++it) acc[it] = MF16(bv[s], ia[s][it], acc[it]);
;         SCHED();
; #pragma unroll
;         for (int i = 0; i < 16; ++i) st[i] = st[i] * cd;
;         bf16x8 bvd[2];
; #pragma unroll
;         for (int s = 0; s < 2; ++s) { const float ck = (dir ? s : 1 - s) ? c32 : 1.f; float e[8];
; #pragma unroll
;             for (int jj = 0; jj < 8; ++jj) e[jj] = bf2f((unsigned short)bv[s][jj]) * (kd8[jj] * ck);
;             u32x4 bw; bw.x = cvtpk(e[0], e[1]); bw.y = cvtpk(e[2], e[3]); bw.z = cvtpk(e[4], e[5]); bw.w = cvtpk(e[6], e[7]);
;             bvd[s] = __builtin_bit_cast(bf16x8, bw); }
; #pragma unroll
;         for (int u = 0; u < 8; ++u) { if (u < 7) LDS_U((u + 1) & 1, u + 1); SCHED();
;             __builtin_amdgcn_s_setprio(1);
; #pragma unroll
;             for (int k = 0; k < 4; ++k) st[4 * (u & 3) + k] = MF16(cat(ua[u & 1][k][0], ua[u & 1][k][1]), bvd[u >> 2], st[4 * (u & 3) + k]);
	ds_read_b64_tr_b16 v[140:141], v232
	ds_read_b64_tr_b16 v[142:143], v232 offset:1088
	ds_read_b64_tr_b16 v[136:137], v232 offset:8704
	ds_read_b64_tr_b16 v[138:139], v232 offset:9792
	ds_read_b128 v[144:147], v233
	ds_read_b128 v[148:151], v233 offset:64
	ds_read_b128 v[152:155], v233 offset:2304
	ds_read_b128 v[156:159], v233 offset:2368
	ds_read_b128 v[236:239], v233 offset:4608
	ds_read_b128 v[240:243], v233 offset:4672
	ds_read_b128 v[244:247], v233 offset:6912
	ds_read_b128 v[248:251], v233 offset:6976
	v_add_u32_e32 v235, v204, v203
	ds_read_b64_tr_b16 v[128:129], v235 offset:36864
	ds_read_b64_tr_b16 v[130:131], v235 offset:39168
	ds_read_b64_tr_b16 v[126:127], v235 offset:39232
	ds_read_b64_tr_b16 v[124:125], v235 offset:36928
	ds_read_b64_tr_b16 v[132:133], v234 offset:36896
	ds_read_b64_tr_b16 v[134:135], v234 offset:39200
	ds_read_b64_tr_b16 v[122:123], v234 offset:39264
	ds_read_b64_tr_b16 v[120:121], v234 offset:36960
	v_pk_mul_f32 v[106:107], v[180:181], v[106:107]
	v_pk_mul_f32 v[104:105], v[178:179], v[104:105]
	v_pk_mul_f32 v[114:115], v[188:189], v[114:115]
	v_pk_mul_f32 v[112:113], v[186:187], v[112:113]
	s_waitcnt lgkmcnt(14)
	v_mfma_f32_16x16x32_bf16 v[104:107], v[140:143], v[144:147], v[104:107]
	v_mul_f32_e64 v110, v184, v110
	v_mul_f32_e64 v111, v185, v111
	v_pk_mul_f32 v[108:109], v[182:183], v[108:109]
	s_waitcnt lgkmcnt(11)
	v_mfma_f32_16x16x32_bf16 v[144:147], v[140:143], v[236:239], v[112:115]
	s_nop 2
	v_mul_f32_e64 v114, v192, v118
	v_mul_f32_e64 v115, v193, v119
	v_pk_mul_f32 v[112:113], v[190:191], v[116:117]
	v_mfma_f32_16x16x32_bf16 v[108:111], v[140:143], v[152:155], v[108:111]
	s_waitcnt lgkmcnt(9)
	v_mfma_f32_16x16x32_bf16 v[152:155], v[140:143], v[244:247], v[112:115]
	v_mfma_f32_16x16x32_bf16 v[116:119], v[136:139], v[148:151], v[104:107]
	v_mfma_f32_16x16x32_bf16 v[112:115], v[136:139], v[156:159], v[108:111]
	v_mfma_f32_16x16x32_bf16 v[108:111], v[136:139], v[240:243], v[144:147]
	s_waitcnt lgkmcnt(8)
	v_mfma_f32_16x16x32_bf16 v[104:107], v[136:139], v[248:251], v[152:155]
	v_mov_b32_e32 v165, v164
	s_nop 1
	v_pk_mul_f32 v[154:155], v[164:165], v[46:47]
	v_pk_mul_f32 v[152:153], v[174:175], v[44:45]
	v_pk_mul_f32 v[46:47], v[164:165], v[70:71]
	v_pk_mul_f32 v[44:45], v[174:175], v[68:69]
	v_pk_mul_f32 v[158:159], v[164:165], v[58:59]
	v_pk_mul_f32 v[156:157], v[174:175], v[56:57]
	v_pk_mul_f32 v[70:71], v[164:165], v[82:83]
	v_pk_mul_f32 v[68:69], v[174:175], v[80:81]
	v_pk_mul_f32 v[82:83], v[164:165], v[78:79]
	v_pk_mul_f32 v[80:81], v[174:175], v[76:77]
	v_pk_mul_f32 v[58:59], v[164:165], v[94:95]
	v_pk_mul_f32 v[56:57], v[174:175], v[92:93]
	v_pk_mul_f32 v[78:79], v[164:165], v[86:87]
	v_pk_mul_f32 v[76:77], v[174:175], v[84:85]
	v_lshlrev_b32_e32 v84, 16, v140
	v_and_b32_e32 v85, 0xffff0000, v140
	v_lshlrev_b32_e32 v86, 16, v141
	v_and_b32_e32 v87, 0xffff0000, v141
	v_lshlrev_b32_e32 v92, 16, v142
	v_and_b32_e32 v93, 0xffff0000, v142
	v_lshlrev_b32_e32 v94, 16, v143
	v_and_b32_e32 v95, 0xffff0000, v143
	v_mul_f32_e32 v84, v208, v84
	v_mul_f32_e32 v85, v209, v85
	v_mul_f32_e32 v86, v210, v86
	v_mul_f32_e32 v87, v211, v87
	v_mul_f32_e32 v92, v212, v92
	v_mul_f32_e32 v93, v213, v93
	v_mul_f32_e32 v94, v214, v94
	v_mul_f32_e32 v95, v215, v95
	v_pk_mul_f32 v[146:147], v[164:165], v[50:51]
	v_pk_mul_f32 v[144:145], v[174:175], v[48:49]
	v_pk_mul_f32 v[50:51], v[164:165], v[90:91]
	v_pk_mul_f32 v[48:49], v[174:175], v[88:89]
	v_pk_mul_f32 v[90:91], v[164:165], v[74:75]
	v_pk_mul_f32 v[88:89], v[174:175], v[72:73]
	v_pk_mul_f32 v[74:75], v[164:165], v[98:99]
	v_pk_mul_f32 v[72:73], v[174:175], v[96:97]
	v_cvt_pk_bf16_f32 v84, v84, v85
	v_cvt_pk_bf16_f32 v85, v86, v87
	v_cvt_pk_bf16_f32 v86, v92, v93
	v_cvt_pk_bf16_f32 v87, v94, v95
	v_lshlrev_b32_e32 v92, 16, v136
	v_and_b32_e32 v93, 0xffff0000, v136
	v_lshlrev_b32_e32 v94, 16, v137
	v_and_b32_e32 v95, 0xffff0000, v137
	v_lshlrev_b32_e32 v96, 16, v138
	v_and_b32_e32 v97, 0xffff0000, v138
	v_lshlrev_b32_e32 v98, 16, v139
	v_and_b32_e32 v99, 0xffff0000, v139
	v_mul_f32_e32 v92, v216, v92
	v_mul_f32_e32 v93, v217, v93
	v_mul_f32_e32 v94, v218, v94
	v_mul_f32_e32 v95, v219, v95
	v_mul_f32_e32 v96, v220, v96
	v_mul_f32_e32 v97, v221, v97
	v_mul_f32_e32 v98, v222, v98
	v_mul_f32_e32 v99, v223, v99
	v_pk_mul_f32 v[150:151], v[164:165], v[62:63]
	v_pk_mul_f32 v[148:149], v[174:175], v[60:61]
	v_pk_mul_f32 v[62:63], v[164:165], v[102:103]
	v_pk_mul_f32 v[60:61], v[174:175], v[100:101]
	v_cvt_pk_bf16_f32 v100, v92, v93
	v_cvt_pk_bf16_f32 v101, v94, v95
	v_cvt_pk_bf16_f32 v102, v96, v97
	v_cvt_pk_bf16_f32 v103, v98, v99
	ds_read_b64_tr_b16 v[92:93], v235 offset:36992
	ds_read_b64_tr_b16 v[94:95], v235 offset:39296
	ds_read_b64_tr_b16 v[96:97], v234 offset:37024
	ds_read_b64_tr_b16 v[98:99], v234 offset:39328
	ds_read_b64_tr_b16 v[136:137], v235 offset:37056
	ds_read_b64_tr_b16 v[138:139], v235 offset:39360
	ds_read_b64_tr_b16 v[140:141], v234 offset:37088
	ds_read_b64_tr_b16 v[142:143], v234 offset:39392
	v_pk_mul_f32 v[42:43], v[164:165], v[42:43]
	v_pk_mul_f32 v[40:41], v[174:175], v[40:41]
	v_pk_mul_f32 v[54:55], v[164:165], v[54:55]
	v_pk_mul_f32 v[52:53], v[174:175], v[52:53]
	v_pk_mul_f32 v[66:67], v[164:165], v[66:67]
	v_pk_mul_f32 v[64:65], v[174:175], v[64:65]
	s_setprio 1
	s_waitcnt lgkmcnt(14)
	v_mfma_f32_16x16x32_bf16 v[40:43], v[128:131], v[84:87], v[40:43]
	s_waitcnt lgkmcnt(10)
	v_mfma_f32_16x16x32_bf16 v[52:55], v[132:135], v[84:87], v[52:55]
	v_mfma_f32_16x16x32_bf16 v[124:127], v[124:127], v[84:87], v[144:147]
	s_waitcnt lgkmcnt(8)
; #define LAS __attribute__((address_space(3)))
; __device__ __forceinline__ unsigned cvtpk(float lo, float hi) { unsigned r; asm volatile("v_cvt_pk_bf16_f32 %0, %1, %2" : "=v"(r) : "v"(lo), "v"(hi)); return r; }
; __device__ __forceinline__ bf16x8 cat(s16x4 a, s16x4 b) { return (bf16x8){a[0], a[1], a[2], a[3], b[0], b[1], b[2], b[3]}; }
; #define MF16(a, b, c) __builtin_amdgcn_mfma_f32_16x16x32_bf16((a), (b), (c), 0, 0, 0)
; #define RBAR() do { asm volatile("s_waitcnt lgkmcnt(0)" ::: "memory"); __builtin_amdgcn_s_barrier(); asm volatile("" ::: "memory"); } while (0)
; __device__ __forceinline__ unsigned cvtpk(float lo, float hi) { unsigned r; asm volatile("v_cvt_pk_bf16_f32 %0, %1, %2" : "=v"(r) : "v"(lo), "v"(hi)); return r; }
; #define SCHED() __builtin_amdgcn_sched_barrier(0)
; #define LDS_U(buf, u) do { _Pragma("unroll") for (int k = 0; k < 4; ++k) { LAS unsigned char* pb = ((k & 1) ? pKo : pKe) + 32 * ((u) >> 2) * RSQ + 32 * (4 * ((u) & 3) + k); ua[buf][k][0] = trd(pb); ua[buf][k][1] = trd(pb + 4 * RSQ); } } while (0)
; __device__ __forceinline__ void ret_item(LAS unsigned char* lds, const bf16_t* proj, bf16_t* OD, int b, int h, int dir, int vs, float lg2) {
;     ...
;         for (int k = 0; k < 4; ++k) { *(LAS bf16x8*)(wQ + 16 * k * RSQ) = pq[k];
;             *(LAS s16x4*)(wK0 + 16 * k * RSQ) = (s16x4){pk[k][0], pk[k][1], pk[k][2], pk[k][3]}; *(LAS s16x4*)(wK1 + 16 * k * RSQ) = (s16x4){pk[k][4], pk[k][5], pk[k][6], pk[k][7]}; }
; #pragma unroll
;         for (int k = 0; k < 2; ++k) *(LAS bf16x8*)(lds + VS + (vrow + 32 * k) * RSV + vpc * 16) = pv[k];
;     ...
;         for (int u = 0; u < 8; ++u) { if (u < 7) LDS_U((u + 1) & 1, u + 1); SCHED();
;             __builtin_amdgcn_s_setprio(1);
; #pragma unroll
;             for (int k = 0; k < 4; ++k) st[4 * (u & 3) + k] = MF16(cat(ua[u & 1][k][0], ua[u & 1][k][1]), bvd[u >> 2], st[4 * (u & 3) + k]);
;             __builtin_amdgcn_s_setprio(0); SCHED(); }
;     ...
; #pragma unroll
;         for (int it = 0; it < 4; ++it) { u32x2 w; w.x = cvtpk(acc[it][0], acc[it][1]); w.y = cvtpk(acc[it][2], acc[it][3]); *(u32x2*)(Og + (t0 + 16 * it + l15) * 4096) = w; }
;         RBAR();
	v_mfma_f32_16x16x32_bf16 v[120:123], v[120:123], v[84:87], v[152:155]
	s_setprio 0
	ds_read_b64_tr_b16 v[128:129], v235 offset:37120
	ds_read_b64_tr_b16 v[130:131], v235 offset:39424
	ds_read_b64_tr_b16 v[134:135], v235 offset:39488
	ds_read_b64_tr_b16 v[132:133], v235 offset:37184
	ds_read_b64_tr_b16 v[144:145], v234 offset:37152
	ds_read_b64_tr_b16 v[146:147], v234 offset:39456
	ds_read_b64_tr_b16 v[154:155], v234 offset:39520
	ds_read_b64_tr_b16 v[152:153], v234 offset:37216
	s_setprio 1
	s_waitcnt lgkmcnt(14)
	v_mfma_f32_16x16x32_bf16 v[92:95], v[92:95], v[84:87], v[44:47]
	s_waitcnt lgkmcnt(12)
	v_mfma_f32_16x16x32_bf16 v[64:67], v[96:99], v[84:87], v[64:67]
	s_waitcnt lgkmcnt(10)
	v_mfma_f32_16x16x32_bf16 v[96:99], v[136:139], v[84:87], v[148:151]
	s_waitcnt lgkmcnt(8)
	v_mfma_f32_16x16x32_bf16 v[136:139], v[140:143], v[84:87], v[156:159]
	s_setprio 0
	ds_read_b64_tr_b16 v[44:45], v235 offset:37248
	ds_read_b64_tr_b16 v[46:47], v235 offset:39552
	ds_read_b64_tr_b16 v[142:143], v235 offset:39616
	ds_read_b64_tr_b16 v[140:141], v235 offset:37312
	ds_read_b64_tr_b16 v[148:149], v234 offset:37280
	ds_read_b64_tr_b16 v[150:151], v234 offset:39584
	ds_read_b64_tr_b16 v[158:159], v234 offset:39648
	ds_read_b64_tr_b16 v[156:157], v234 offset:37344
	s_setprio 1
	s_waitcnt lgkmcnt(14)
	v_mfma_f32_16x16x32_bf16 v[128:131], v[128:131], v[84:87], v[48:51]
	s_waitcnt lgkmcnt(10)
	v_mfma_f32_16x16x32_bf16 v[144:147], v[144:147], v[84:87], v[68:71]
	v_mfma_f32_16x16x32_bf16 v[132:135], v[132:135], v[84:87], v[80:83]
	s_waitcnt lgkmcnt(8)
	v_mfma_f32_16x16x32_bf16 v[152:155], v[152:155], v[84:87], v[88:91]
	s_setprio 0
	ds_read_b64_tr_b16 v[48:49], v235 offset:55296
	ds_read_b64_tr_b16 v[50:51], v235 offset:57600
	ds_read_b64_tr_b16 v[70:71], v235 offset:57664
	ds_read_b64_tr_b16 v[68:69], v235 offset:55360
	ds_read_b64_tr_b16 v[80:81], v234 offset:55328
	ds_read_b64_tr_b16 v[82:83], v234 offset:57632
	ds_read_b64_tr_b16 v[90:91], v234 offset:57696
	ds_read_b64_tr_b16 v[88:89], v234 offset:55392
	s_setprio 1
	s_waitcnt lgkmcnt(14)
	v_mfma_f32_16x16x32_bf16 v[236:239], v[44:47], v[84:87], v[56:59]
	s_waitcnt lgkmcnt(10)
	v_mfma_f32_16x16x32_bf16 v[148:151], v[148:151], v[84:87], v[76:79]
	v_mfma_f32_16x16x32_bf16 v[140:143], v[140:143], v[84:87], v[72:75]
	s_waitcnt lgkmcnt(8)
	v_mfma_f32_16x16x32_bf16 v[156:159], v[156:159], v[84:87], v[60:63]
	s_setprio 0
	ds_read_b64_tr_b16 v[56:57], v235 offset:55424
	ds_read_b64_tr_b16 v[58:59], v235 offset:57728
	ds_read_b64_tr_b16 v[62:63], v235 offset:57792
	ds_read_b64_tr_b16 v[60:61], v235 offset:55488
	ds_read_b64_tr_b16 v[72:73], v234 offset:55456
	ds_read_b64_tr_b16 v[74:75], v234 offset:57760
	ds_read_b64_tr_b16 v[78:79], v234 offset:57824
	ds_read_b64_tr_b16 v[76:77], v234 offset:55520
	s_setprio 1
	s_waitcnt lgkmcnt(14)
	v_mfma_f32_16x16x32_bf16 v[40:43], v[48:51], v[100:103], v[40:43]
	s_waitcnt lgkmcnt(10)
	v_mfma_f32_16x16x32_bf16 v[52:55], v[80:83], v[100:103], v[52:55]
	v_mfma_f32_16x16x32_bf16 v[48:51], v[68:71], v[100:103], v[124:127]
	s_waitcnt lgkmcnt(8)
	v_mfma_f32_16x16x32_bf16 v[44:47], v[88:91], v[100:103], v[120:123]
	s_setprio 0
	ds_read_b64_tr_b16 v[80:81], v235 offset:55552
	ds_read_b64_tr_b16 v[82:83], v235 offset:57856
	ds_read_b64_tr_b16 v[86:87], v235 offset:57920
	ds_read_b64_tr_b16 v[84:85], v235 offset:55616
	ds_read_b64_tr_b16 v[120:121], v234 offset:55584
	ds_read_b64_tr_b16 v[122:123], v234 offset:57888
	ds_read_b64_tr_b16 v[126:127], v234 offset:57952
	ds_read_b64_tr_b16 v[124:125], v234 offset:55648
	s_setprio 1
	s_waitcnt lgkmcnt(14)
	v_mfma_f32_16x16x32_bf16 v[68:71], v[56:59], v[100:103], v[92:95]
	s_waitcnt lgkmcnt(10)
	v_mfma_f32_16x16x32_bf16 v[64:67], v[72:75], v[100:103], v[64:67]
	v_mfma_f32_16x16x32_bf16 v[60:63], v[60:63], v[100:103], v[96:99]
	s_waitcnt lgkmcnt(8)
	v_mfma_f32_16x16x32_bf16 v[56:59], v[76:79], v[100:103], v[136:139]
	s_setprio 0
	ds_read_b64_tr_b16 v[92:93], v235 offset:55680
	ds_read_b64_tr_b16 v[94:95], v235 offset:57984
	ds_read_b64_tr_b16 v[98:99], v235 offset:58048
	ds_read_b64_tr_b16 v[96:97], v235 offset:55744
	ds_read_b64_tr_b16 v[136:137], v234 offset:55712
	ds_read_b64_tr_b16 v[138:139], v234 offset:58016
	ds_read_b64_tr_b16 v[242:243], v234 offset:58080
	ds_read_b64_tr_b16 v[240:241], v234 offset:55776
	s_setprio 1
	s_waitcnt lgkmcnt(14)
	v_mfma_f32_16x16x32_bf16 v[88:91], v[80:83], v[100:103], v[128:131]
	s_waitcnt lgkmcnt(10)
	v_mfma_f32_16x16x32_bf16 v[80:83], v[120:123], v[100:103], v[144:147]
	v_mfma_f32_16x16x32_bf16 v[76:79], v[84:87], v[100:103], v[132:135]
	s_waitcnt lgkmcnt(8)
	v_mfma_f32_16x16x32_bf16 v[72:75], v[124:127], v[100:103], v[152:155]
	s_setprio 0
	s_setprio 1
	s_waitcnt lgkmcnt(6)
	v_mfma_f32_16x16x32_bf16 v[92:95], v[92:95], v[100:103], v[236:239]
	s_waitcnt lgkmcnt(2)
	v_mfma_f32_16x16x32_bf16 v[84:87], v[136:139], v[100:103], v[148:151]
	v_mfma_f32_16x16x32_bf16 v[96:99], v[96:99], v[100:103], v[140:143]
	s_waitcnt lgkmcnt(0)
	v_mfma_f32_16x16x32_bf16 v[100:103], v[240:243], v[100:103], v[156:159]
	s_setprio 0
	v_lshl_or_b32 v176, v176, 18, v224
	v_cvt_pk_bf16_f32 v116, v116, v117
	v_cvt_pk_bf16_f32 v117, v118, v119
	v_lshl_add_u64 v[118:119], v[176:177], 1, v[160:161]
	global_store_dwordx2 v[118:119], v[116:117], off
	v_cvt_pk_bf16_f32 v112, v112, v113
	v_cvt_pk_bf16_f32 v113, v114, v115
	v_ashrrev_i32_e32 v115, 31, v176
	v_mov_b32_e32 v114, v176
	v_lshl_add_u64 v[114:115], v[114:115], 1, v[160:161]
	s_mov_b32 s20, 0x20000
	v_add_co_u32_e32 v116, vcc, s20, v114
	s_mov_b32 s20, 0x40000
	s_nop 0
	v_addc_co_u32_e32 v117, vcc, 0, v115, vcc
	global_store_dwordx2 v[116:117], v[112:113], off
	v_cvt_pk_bf16_f32 v108, v108, v109
	v_cvt_pk_bf16_f32 v109, v110, v111
	v_add_co_u32_e32 v110, vcc, s20, v114
	s_add_i32 s19, s19, -1
	s_nop 0
	v_addc_co_u32_e32 v111, vcc, 0, v115, vcc
	global_store_dwordx2 v[110:111], v[108:109], off
	v_cvt_pk_bf16_f32 v104, v104, v105
	v_cvt_pk_bf16_f32 v105, v106, v107
	v_add_co_u32_e32 v106, vcc, s65, v114
	s_add_i32 s16, s16, 1
	s_nop 0
	v_addc_co_u32_e32 v107, vcc, 0, v115, vcc
	global_store_dwordx2 v[106:107], v[104:105], off
	s_waitcnt lgkmcnt(0)
	s_barrier
	s_cmp_lg_u32 s19, -2
	s_cbranch_scc0 .LBB0_138
.LBB0_141:
	v_add_co_u32_e64 v104, s[20:21], s19, 1
	s_and_b64 vcc, exec, s[20:21]
	s_waitcnt vmcnt(13)
	ds_write_b128 v225, v[0:3]
	s_waitcnt vmcnt(12)
	ds_write_b64 v226, v[4:5] offset:36864
	s_waitcnt vmcnt(11)
	ds_write_b128 v225, v[8:11] offset:9216
	s_waitcnt vmcnt(10)
	ds_write_b64 v226, v[12:13] offset:46080
	ds_write2st64_b64 v227, v[6:7], v[14:15] offset0:72 offset1:90
	s_waitcnt vmcnt(9)
	ds_write_b128 v225, v[16:19] offset:18432
	s_waitcnt vmcnt(8)
	ds_write_b64 v226, v[20:21] offset:55296
	s_waitcnt vmcnt(7)
	ds_write_b128 v225, v[24:27] offset:27648
	s_waitcnt vmcnt(6)
	ds_write_b64 v226, v[28:29] offset:64512
	ds_write2st64_b64 v227, v[22:23], v[30:31] offset0:108 offset1:126
	s_waitcnt vmcnt(5)
	ds_write_b128 v228, v[32:35]
	s_waitcnt vmcnt(4)
	ds_write_b128 v228, v[36:39] offset:8704
	s_branch .LBB0_140
